# adds E11/E12: band attention (groups 0,1) waves skip steps whose two tiles are fully masked for them (exact zeros), stacked on E1,E4-E9
# speedup vs baseline: 1.0056x; 1.0036x over previous
.LBB0_637:
	s_lshl_b64 s[28:29], s[2:3], s22
	v_lshl_add_u64 v[64:65], s[28:29], 1, v[180:181]
	s_add_i32 s0, s4, s75
	s_mov_b32 s28, m0
	s_mov_b32 m0, s0
	s_nop 0
	global_load_lds_dwordx4 v[64:65], off
	s_mov_b32 m0, s28
	s_sub_i32 s28, s23, 0x80
	s_max_i32 s28, s28, 0
	s_sub_i32 s29, s76, 63
	s_cmp_le_i32 s29, s28
	s_cbranch_scc1 .Lxa_idle
	s_sub_i32 s29, s76, 0xde
	s_cmp_gt_i32 s29, s23
	s_cbranch_scc1 .Lxa_idle
	v_add_u32_e32 v164, s1, v190
	ds_read_b64_tr_b16 v[160:161], v164 offset:24576
	ds_read_b64_tr_b16 v[162:163], v164 offset:25088
	s_waitcnt lgkmcnt(9)
	v_mfma_f32_32x32x16_bf16 v[80:95], v[156:159], v[124:127], 0
	v_add_f32_e32 v64, v48, v49
	v_add_f32_e32 v64, v50, v64
	v_add_f32_e32 v64, v51, v64
	v_add_f32_e32 v64, v52, v64
	v_add_f32_e32 v64, v53, v64
	v_cvt_pk_bf16_f32 v116, v48, v49
	v_cvt_pk_bf16_f32 v117, v50, v51
	ds_read_b64_tr_b16 v[156:157], v164 offset:28672
	ds_read_b64_tr_b16 v[158:159], v164 offset:29184
	v_add_f32_e32 v48, v54, v64
	s_waitcnt lgkmcnt(10)
	v_mfma_f32_32x32x16_bf16 v[64:79], v[148:151], v[124:127], 0
	v_add_f32_e32 v48, v55, v48
	v_add_f32_e32 v48, v56, v48
	v_add_f32_e32 v96, v57, v48
	v_cvt_pk_bf16_f32 v118, v52, v53
	v_cvt_pk_bf16_f32 v119, v54, v55
	ds_read_b64_tr_b16 v[48:49], v164 offset:25600
	ds_read_b64_tr_b16 v[50:51], v164 offset:26112
	s_waitcnt lgkmcnt(11)
	v_mfma_f32_32x32x16_bf16 v[80:95], v[152:155], v[120:123], v[80:95]
	v_add_f32_e32 v52, v58, v96
	v_add_f32_e32 v52, v59, v52
	v_add_f32_e32 v52, v60, v52
	v_add_f32_e32 v96, v61, v52
	v_cvt_pk_bf16_f32 v108, v56, v57
	v_cvt_pk_bf16_f32 v109, v58, v59
	ds_read_b64_tr_b16 v[52:53], v164 offset:29696
	ds_read_b64_tr_b16 v[54:55], v164 offset:30208
	s_waitcnt lgkmcnt(12)
	v_mfma_f32_32x32x16_bf16 v[64:79], v[144:147], v[120:123], v[64:79]
	v_add_f32_e32 v56, v62, v96
	v_add_f32_e32 v56, v63, v56
	v_add_f32_e32 v56, v32, v56
	v_add_f32_e32 v96, v33, v56
	v_cvt_pk_bf16_f32 v110, v60, v61
	v_cvt_pk_bf16_f32 v111, v62, v63
	ds_read_b64_tr_b16 v[56:57], v164 offset:26624
	ds_read_b64_tr_b16 v[58:59], v164 offset:27136
	s_waitcnt lgkmcnt(13)
	v_mfma_f32_32x32x16_bf16 v[80:95], v[140:143], v[112:115], v[80:95]
	v_add_f32_e32 v60, v34, v96
	v_add_f32_e32 v60, v35, v60
	v_add_f32_e32 v60, v36, v60
	v_add_f32_e32 v60, v37, v60
	v_cvt_pk_bf16_f32 v100, v32, v33
	v_cvt_pk_bf16_f32 v101, v34, v35
	ds_read_b64_tr_b16 v[32:33], v164 offset:30720
	ds_read_b64_tr_b16 v[34:35], v164 offset:31232
	s_waitcnt lgkmcnt(14)
	v_mfma_f32_32x32x16_bf16 v[64:79], v[136:139], v[112:115], v[64:79]
	v_add_f32_e32 v60, v38, v60
	v_add_f32_e32 v60, v39, v60
	v_add_f32_e32 v60, v40, v60
	v_add_f32_e32 v60, v41, v60
	v_cvt_pk_bf16_f32 v102, v36, v37
	v_cvt_pk_bf16_f32 v103, v38, v39
	ds_read_b64_tr_b16 v[36:37], v164 offset:27648
	ds_read_b64_tr_b16 v[38:39], v164 offset:28160
	s_waitcnt lgkmcnt(14)
	v_mfma_f32_32x32x16_bf16 v[80:95], v[132:135], v[104:107], v[80:95]
	v_add_f32_e32 v60, v42, v60
	v_add_f32_e32 v60, v43, v60
	v_add_f32_e32 v60, v44, v60
	v_add_f32_e32 v60, v45, v60
	v_cvt_pk_bf16_f32 v96, v40, v41
	v_cvt_pk_bf16_f32 v97, v42, v43
	ds_read_b64_tr_b16 v[40:41], v164 offset:31744
	ds_read_b64_tr_b16 v[42:43], v164 offset:32256
	v_mfma_f32_32x32x16_bf16 v[64:79], v[128:131], v[104:107], v[64:79]
	v_add_f32_e32 v60, v46, v60
	v_add_f32_e32 v60, v47, v60
	v_add_f32_e32 v191, 0, v60
	v_cvt_pk_bf16_f32 v98, v44, v45
	v_cvt_pk_bf16_f32 v99, v46, v47
	v_add_u32_e32 v203, s76, v184
	s_sub_i32 s0, s76, 64
	v_add_u32_e32 v149, 0xffffff81, v203
	s_cmp_le_i32 s0, s23
	v_add_u32_e32 v150, 0xffffffa1, v203
	v_add_u32_e32 v148, 0xffffffa2, v203
	v_add_u32_e32 v146, 0xffffff83, v203
	v_add_u32_e32 v147, 0xffffffa3, v203
	v_add_u32_e32 v144, 0xffffff84, v203
	v_add_u32_e32 v145, 0xffffffa4, v203
	v_add_u32_e32 v142, 0xffffff89, v203
	v_add_u32_e32 v143, 0xffffffa9, v203
	v_add_u32_e32 v140, 0xffffff8a, v203
	v_add_u32_e32 v141, 0xffffffaa, v203
	v_add_u32_e32 v138, 0xffffff8b, v203
	v_add_u32_e32 v139, 0xffffffab, v203
	v_add_u32_e32 v136, 0xffffff8c, v203
	v_add_u32_e32 v137, 0xffffffac, v203
	v_add_u32_e32 v134, 0xffffff91, v203
	v_add_u32_e32 v135, 0xffffffb1, v203
	v_add_u32_e32 v132, 0xffffff92, v203
	v_add_u32_e32 v133, 0xffffffb2, v203
	v_add_u32_e32 v130, 0xffffff93, v203
	v_add_u32_e32 v131, 0xffffffb3, v203
	v_add_u32_e32 v128, 0xffffff94, v203
	v_add_u32_e32 v129, 0xffffffb4, v203
	v_add_u32_e32 v62, 0xffffff99, v203
	v_add_u32_e32 v63, 0xffffffb9, v203
	v_add_u32_e32 v60, 0xffffff9a, v203
	v_add_u32_e32 v61, 0xffffffba, v203
	v_add_u32_e32 v46, 0xffffff9b, v203
	v_add_u32_e32 v47, 0xffffffbb, v203
	v_add_u32_e32 v44, 0xffffff9c, v203
	v_add_u32_e32 v45, 0xffffffbc, v203
	s_cbranch_scc1 .LBB0_641
	v_cmp_le_i32_e64 s[0:1], v150, v186
	v_cmp_le_i32_e64 s[38:39], v148, v186
	v_cmp_le_i32_e64 s[40:41], v147, v186
	v_cmp_le_i32_e64 s[42:43], v145, v186
	v_cmp_le_i32_e64 s[44:45], v143, v186
	v_cmp_le_i32_e64 s[46:47], v141, v186
	v_cmp_le_i32_e64 s[50:51], v139, v186
	v_cmp_le_i32_e64 s[52:53], v137, v186
	v_cmp_le_i32_e64 s[54:55], v135, v186
	v_cmp_le_i32_e64 s[56:57], v133, v186
	v_cmp_le_i32_e64 s[58:59], v131, v186
	v_cmp_le_i32_e64 s[60:61], v129, v186
	v_cmp_le_i32_e64 s[62:63], v63, v186
	v_cmp_le_i32_e64 s[64:65], v61, v186
	v_cmp_le_i32_e64 s[66:67], v47, v186
	v_cmp_le_i32_e32 vcc, v149, v186
	v_cndmask_b32_e64 v64, v240, v64, s[0:1]
	v_cmp_lt_i32_e64 s[0:1], v149, v186
	v_cndmask_b32_e64 v65, v240, v65, s[38:39]
	v_cmp_le_i32_e64 s[38:39], v146, v186
	v_cndmask_b32_e64 v66, v240, v66, s[40:41]
	v_cmp_le_i32_e64 s[40:41], v144, v186
	v_cndmask_b32_e64 v67, v240, v67, s[42:43]
	v_cmp_le_i32_e64 s[42:43], v142, v186
	v_cndmask_b32_e64 v68, v240, v68, s[44:45]
	v_cmp_le_i32_e64 s[44:45], v140, v186
	v_cndmask_b32_e64 v69, v240, v69, s[46:47]
	v_cmp_le_i32_e64 s[46:47], v138, v186
	v_cndmask_b32_e64 v70, v240, v70, s[50:51]
	v_cmp_le_i32_e64 s[50:51], v136, v186
	v_cndmask_b32_e64 v71, v240, v71, s[52:53]
	v_cmp_le_i32_e64 s[52:53], v134, v186
	v_cndmask_b32_e64 v72, v240, v72, s[54:55]
	v_cmp_le_i32_e64 s[54:55], v132, v186
	v_cndmask_b32_e64 v73, v240, v73, s[56:57]
	v_cmp_le_i32_e64 s[56:57], v130, v186
	v_cndmask_b32_e64 v74, v240, v74, s[58:59]
	v_cmp_le_i32_e64 s[58:59], v128, v186
	v_cndmask_b32_e64 v75, v240, v75, s[60:61]
	v_cmp_le_i32_e64 s[60:61], v62, v186
	v_cndmask_b32_e64 v76, v240, v76, s[62:63]
	v_cmp_le_i32_e64 s[62:63], v60, v186
	v_cndmask_b32_e64 v77, v240, v77, s[64:65]
	v_cmp_le_i32_e64 s[64:65], v46, v186
	v_cndmask_b32_e64 v78, v240, v78, s[66:67]
	v_cmp_le_i32_e64 s[66:67], v44, v186
	v_cmp_gt_i32_e64 s[68:69], v45, v186
	s_and_saveexec_b64 s[28:29], s[68:69]
	s_mov_b32 s68, 0xff800000
	v_mov_b32_e32 v79, s68
	s_or_b64 exec, exec, s[28:29]
	v_cndmask_b32_e64 v81, v240, v81, s[0:1]
	v_cndmask_b32_e32 v80, v240, v80, vcc
	v_cndmask_b32_e64 v82, v240, v82, s[38:39]
	v_cndmask_b32_e64 v83, v240, v83, s[40:41]
	v_cndmask_b32_e64 v84, v240, v84, s[42:43]
	v_cndmask_b32_e64 v85, v240, v85, s[44:45]
	v_cndmask_b32_e64 v86, v240, v86, s[46:47]
	v_cndmask_b32_e64 v87, v240, v87, s[50:51]
	v_cndmask_b32_e64 v88, v240, v88, s[52:53]
	v_cndmask_b32_e64 v89, v240, v89, s[54:55]
	v_cndmask_b32_e64 v90, v240, v90, s[56:57]
	v_cndmask_b32_e64 v91, v240, v91, s[58:59]
	v_cndmask_b32_e64 v92, v240, v92, s[60:61]
	v_cndmask_b32_e64 v93, v240, v93, s[62:63]
	v_cndmask_b32_e64 v94, v240, v94, s[64:65]
	v_cndmask_b32_e64 v95, v240, v95, s[66:67]

.Lxa_join:
	s_mov_b64 s[0:1], -1
	s_and_b64 vcc, exec, s[34:35]
	s_cbranch_vccz .LBB0_651
	s_add_i32 s0, s2, -1
	s_cmp_ge_u32 s0, s5
	s_mov_b64 s[0:1], -1
	s_cbranch_scc0 .LBB0_648
	s_waitcnt vmcnt(0) lgkmcnt(0)
	s_barrier
	s_mov_b64 s[0:1], 0

.LBB0_657:
	s_sub_i32 s0, s23, 0x80
	s_max_i32 s0, s0, 0
	s_add_i32 s1, s76, 1
	s_cmp_le_i32 s1, s0
	s_cbranch_scc1 .Lxb_idle
	s_sub_i32 s1, s76, 0x9e
	s_cmp_gt_i32 s1, s23
	s_cbranch_scc1 .Lxb_idle
	v_add_u32_e32 v194, s72, v190
	ds_read_b64_tr_b16 v[168:169], v194 offset:24576
	ds_read_b64_tr_b16 v[170:171], v194 offset:25088
	s_waitcnt lgkmcnt(9)
	v_mfma_f32_32x32x16_bf16 v[48:63], v[156:159], v[124:127], 0
	v_add_f32_e32 v32, v80, v81
	v_add_f32_e32 v32, v82, v32
	v_add_f32_e32 v32, v83, v32
	v_add_f32_e32 v32, v84, v32
	v_add_f32_e32 v32, v85, v32
	v_cvt_pk_bf16_f32 v116, v80, v81
	v_cvt_pk_bf16_f32 v117, v82, v83
	ds_read_b64_tr_b16 v[164:165], v194 offset:28672
	ds_read_b64_tr_b16 v[166:167], v194 offset:29184
	v_add_f32_e32 v32, v86, v32
	v_add_f32_e32 v32, v87, v32
	v_add_f32_e32 v32, v88, v32
	v_add_f32_e32 v80, v89, v32
	s_waitcnt lgkmcnt(10)
	v_mfma_f32_32x32x16_bf16 v[32:47], v[148:151], v[124:127], 0
	v_cvt_pk_bf16_f32 v118, v84, v85
	v_cvt_pk_bf16_f32 v119, v86, v87
	ds_read_b64_tr_b16 v[160:161], v194 offset:25600
	ds_read_b64_tr_b16 v[162:163], v194 offset:26112
	s_waitcnt lgkmcnt(11)
	v_mfma_f32_32x32x16_bf16 v[48:63], v[152:155], v[120:123], v[48:63]
	v_add_f32_e32 v80, v90, v80
	v_add_f32_e32 v80, v91, v80
	v_add_f32_e32 v80, v92, v80
	v_add_f32_e32 v80, v93, v80
	v_cvt_pk_bf16_f32 v108, v88, v89
	v_cvt_pk_bf16_f32 v109, v90, v91
	ds_read_b64_tr_b16 v[88:89], v194 offset:29696
	ds_read_b64_tr_b16 v[90:91], v194 offset:30208
	s_waitcnt lgkmcnt(12)
	v_mfma_f32_32x32x16_bf16 v[32:47], v[144:147], v[120:123], v[32:47]
	v_add_f32_e32 v80, v94, v80
	v_add_f32_e32 v80, v95, v80
	v_add_f32_e32 v80, v64, v80
	v_add_f32_e32 v80, v65, v80
	v_cvt_pk_bf16_f32 v110, v92, v93
	v_cvt_pk_bf16_f32 v111, v94, v95
	ds_read_b64_tr_b16 v[84:85], v194 offset:26624
	ds_read_b64_tr_b16 v[86:87], v194 offset:27136
	s_waitcnt lgkmcnt(13)
	v_mfma_f32_32x32x16_bf16 v[48:63], v[140:143], v[112:115], v[48:63]
	v_add_f32_e32 v80, v66, v80
	v_add_f32_e32 v80, v67, v80
	v_add_f32_e32 v80, v68, v80
	v_add_f32_e32 v92, v69, v80
	v_cvt_pk_bf16_f32 v100, v64, v65
	v_cvt_pk_bf16_f32 v101, v66, v67
	ds_read_b64_tr_b16 v[80:81], v194 offset:30720
	ds_read_b64_tr_b16 v[82:83], v194 offset:31232
	s_waitcnt lgkmcnt(14)
	v_mfma_f32_32x32x16_bf16 v[32:47], v[136:139], v[112:115], v[32:47]
	v_add_f32_e32 v64, v70, v92
	v_add_f32_e32 v64, v71, v64
	v_add_f32_e32 v64, v72, v64
	v_add_f32_e32 v64, v73, v64
	v_cvt_pk_bf16_f32 v102, v68, v69
	v_cvt_pk_bf16_f32 v103, v70, v71
	ds_read_b64_tr_b16 v[68:69], v194 offset:27648
	ds_read_b64_tr_b16 v[70:71], v194 offset:28160
	s_waitcnt lgkmcnt(14)
	v_mfma_f32_32x32x16_bf16 v[48:63], v[132:135], v[104:107], v[48:63]
	v_add_f32_e32 v64, v74, v64
	v_add_f32_e32 v64, v75, v64
	v_add_f32_e32 v64, v76, v64
	v_add_f32_e32 v92, v77, v64
	v_cvt_pk_bf16_f32 v96, v72, v73
	v_cvt_pk_bf16_f32 v97, v74, v75
	ds_read_b64_tr_b16 v[64:65], v194 offset:31744
	ds_read_b64_tr_b16 v[66:67], v194 offset:32256
	v_mfma_f32_32x32x16_bf16 v[32:47], v[128:131], v[104:107], v[32:47]
	v_add_f32_e32 v72, v78, v92
	v_add_f32_e32 v72, v79, v72
	v_add_f32_e32 v72, 0, v72
	v_cvt_pk_bf16_f32 v98, v76, v77
	v_cvt_pk_bf16_f32 v99, v78, v79
	v_subrev_u32_e32 v222, 63, v203
	s_cmp_le_i32 s76, s23
	v_subrev_u32_e32 v223, 31, v203
	v_subrev_u32_e32 v221, 30, v203
	v_subrev_u32_e32 v219, 61, v203
	v_subrev_u32_e32 v220, 29, v203
	v_subrev_u32_e32 v217, 60, v203
	v_subrev_u32_e32 v218, 28, v203
	v_subrev_u32_e32 v215, 55, v203
	v_subrev_u32_e32 v216, 23, v203
	v_subrev_u32_e32 v213, 54, v203
	v_subrev_u32_e32 v214, 22, v203
	v_subrev_u32_e32 v211, 53, v203
	v_subrev_u32_e32 v212, 21, v203
	v_subrev_u32_e32 v209, 52, v203
	v_subrev_u32_e32 v210, 20, v203
	v_subrev_u32_e32 v207, 47, v203
	v_add_u32_e32 v208, -15, v203
	v_subrev_u32_e32 v205, 46, v203
	v_add_u32_e32 v206, -14, v203
	v_subrev_u32_e32 v95, 45, v203
	v_add_u32_e32 v204, -13, v203
	v_subrev_u32_e32 v93, 44, v203
	v_add_u32_e32 v94, -12, v203
	v_subrev_u32_e32 v79, 39, v203
	v_add_u32_e32 v92, -7, v203
	v_subrev_u32_e32 v77, 38, v203
	v_add_u32_e32 v78, -6, v203
	v_subrev_u32_e32 v75, 37, v203
	v_add_u32_e32 v76, -5, v203
	v_subrev_u32_e32 v73, 36, v203
	v_add_u32_e32 v74, -4, v203
	s_cbranch_scc1 .LBB0_661
	v_cmp_le_i32_e64 s[0:1], v223, v186
	v_cmp_le_i32_e64 s[38:39], v221, v186
	v_cmp_le_i32_e64 s[40:41], v220, v186
	v_cmp_le_i32_e64 s[42:43], v218, v186
	v_cmp_le_i32_e64 s[44:45], v216, v186
	v_cmp_le_i32_e64 s[46:47], v214, v186
	v_cmp_le_i32_e64 s[50:51], v212, v186
	v_cmp_le_i32_e64 s[52:53], v210, v186
	v_cmp_le_i32_e64 s[54:55], v208, v186
	v_cmp_le_i32_e64 s[56:57], v206, v186
	v_cmp_le_i32_e64 s[58:59], v204, v186
	v_cmp_le_i32_e64 s[60:61], v94, v186
	v_cmp_le_i32_e64 s[62:63], v92, v186
	v_cmp_le_i32_e64 s[64:65], v78, v186
	v_cmp_le_i32_e64 s[66:67], v76, v186
	v_cmp_le_i32_e32 vcc, v222, v186
	v_cndmask_b32_e64 v32, v240, v32, s[0:1]
	v_cmp_lt_i32_e64 s[0:1], v222, v186
	v_cndmask_b32_e64 v33, v240, v33, s[38:39]
	v_cmp_le_i32_e64 s[38:39], v219, v186
	v_cndmask_b32_e64 v34, v240, v34, s[40:41]
	v_cmp_le_i32_e64 s[40:41], v217, v186
	v_cndmask_b32_e64 v35, v240, v35, s[42:43]
	v_cmp_le_i32_e64 s[42:43], v215, v186
	v_cndmask_b32_e64 v36, v240, v36, s[44:45]
	v_cmp_le_i32_e64 s[44:45], v213, v186
	v_cndmask_b32_e64 v37, v240, v37, s[46:47]
	v_cmp_le_i32_e64 s[46:47], v211, v186
	v_cndmask_b32_e64 v38, v240, v38, s[50:51]
	v_cmp_le_i32_e64 s[50:51], v209, v186
	v_cndmask_b32_e64 v39, v240, v39, s[52:53]
	v_cmp_le_i32_e64 s[52:53], v207, v186
	v_cndmask_b32_e64 v40, v240, v40, s[54:55]
	v_cmp_le_i32_e64 s[54:55], v205, v186
	v_cndmask_b32_e64 v41, v240, v41, s[56:57]
	v_cmp_le_i32_e64 s[56:57], v95, v186
	v_cndmask_b32_e64 v42, v240, v42, s[58:59]
	v_cmp_le_i32_e64 s[58:59], v93, v186
	v_cndmask_b32_e64 v43, v240, v43, s[60:61]
	v_cmp_le_i32_e64 s[60:61], v79, v186
	v_cndmask_b32_e64 v44, v240, v44, s[62:63]
	v_cmp_le_i32_e64 s[62:63], v77, v186
	v_cndmask_b32_e64 v45, v240, v45, s[64:65]
	v_cmp_le_i32_e64 s[64:65], v75, v186
	v_cndmask_b32_e64 v46, v240, v46, s[66:67]
	v_cmp_le_i32_e64 s[66:67], v73, v186
	v_cmp_gt_i32_e64 s[68:69], v74, v186
	s_and_saveexec_b64 s[72:73], s[68:69]
	s_mov_b32 s68, 0xff800000
	v_mov_b32_e32 v47, s68
	s_or_b64 exec, exec, s[72:73]
	v_cndmask_b32_e64 v49, v240, v49, s[0:1]
	v_cndmask_b32_e32 v48, v240, v48, vcc
	v_cndmask_b32_e64 v50, v240, v50, s[38:39]
	v_cndmask_b32_e64 v51, v240, v51, s[40:41]
	v_cndmask_b32_e64 v52, v240, v52, s[42:43]
	v_cndmask_b32_e64 v53, v240, v53, s[44:45]
	v_cndmask_b32_e64 v54, v240, v54, s[46:47]
	v_cndmask_b32_e64 v55, v240, v55, s[50:51]
	v_cndmask_b32_e64 v56, v240, v56, s[52:53]
	v_cndmask_b32_e64 v57, v240, v57, s[54:55]
	v_cndmask_b32_e64 v58, v240, v58, s[56:57]
	v_cndmask_b32_e64 v59, v240, v59, s[58:59]
	v_cndmask_b32_e64 v60, v240, v60, s[60:61]
	v_cndmask_b32_e64 v61, v240, v61, s[62:63]
	v_cndmask_b32_e64 v62, v240, v62, s[64:65]
	v_cndmask_b32_e64 v63, v240, v63, s[66:67]

.Lxb_join:
	s_mov_b64 s[0:1], -1
	s_and_b64 vcc, exec, s[28:29]
	s_cbranch_vccz .LBB0_679
	s_and_b64 vcc, exec, s[34:35]
	s_cbranch_vccz .LBB0_676
	s_waitcnt vmcnt(0) lgkmcnt(0)
	s_barrier
	s_mov_b64 s[0:1], 0

.Lxa_idle:
	v_add_u32_e32 v44, s4, v177
	ds_read_b128 v[156:159], v44
	ds_read_b128 v[148:151], v44 offset:512
	ds_read_b128 v[152:155], v44 offset:2048
	ds_read_b128 v[144:147], v44 offset:2560
	ds_read_b128 v[140:143], v44 offset:4096
	ds_read_b128 v[136:139], v44 offset:4608
	ds_read_b128 v[132:135], v44 offset:6144
	ds_read_b128 v[128:131], v44 offset:6656
	v_mov_b32_e32 v64, 0
	v_mov_b32_e32 v65, 0
	v_mov_b32_e32 v66, 0
	v_mov_b32_e32 v67, 0
	v_mov_b32_e32 v68, 0
	v_mov_b32_e32 v69, 0
	v_mov_b32_e32 v70, 0
	v_mov_b32_e32 v71, 0
	v_mov_b32_e32 v72, 0
	v_mov_b32_e32 v73, 0
	v_mov_b32_e32 v74, 0
	v_mov_b32_e32 v75, 0
	v_mov_b32_e32 v76, 0
	v_mov_b32_e32 v77, 0
	v_mov_b32_e32 v78, 0
	v_mov_b32_e32 v79, 0
	v_mov_b32_e32 v80, 0
	v_mov_b32_e32 v81, 0
	v_mov_b32_e32 v82, 0
	v_mov_b32_e32 v83, 0
	v_mov_b32_e32 v84, 0
	v_mov_b32_e32 v85, 0
	v_mov_b32_e32 v86, 0
	v_mov_b32_e32 v87, 0
	v_mov_b32_e32 v88, 0
	v_mov_b32_e32 v89, 0
	v_mov_b32_e32 v90, 0
	v_mov_b32_e32 v91, 0
	v_mov_b32_e32 v92, 0
	v_mov_b32_e32 v93, 0
	v_mov_b32_e32 v94, 0
	v_mov_b32_e32 v95, 0
	v_mov_b32_e32 v191, 0
	v_add_u32_e32 v203, s76, v184
	s_branch .Lxa_join
.Lxb_idle:
	s_andn2_b64 vcc, exec, s[2:3]
	s_cbranch_vccnz .Lxb_nokrd
	v_add_u32_e32 v73, s79, v177
	ds_read_b128 v[156:159], v73
	ds_read_b128 v[148:151], v73 offset:512
	ds_read_b128 v[152:155], v73 offset:2048
	ds_read_b128 v[144:147], v73 offset:2560
	ds_read_b128 v[140:143], v73 offset:4096
	ds_read_b128 v[136:139], v73 offset:4608
	ds_read_b128 v[132:135], v73 offset:6144
	ds_read_b128 v[128:131], v73 offset:6656
.Lxb_nokrd:
	v_mov_b32_e32 v32, 0
	v_mov_b32_e32 v33, 0
	v_mov_b32_e32 v34, 0
	v_mov_b32_e32 v35, 0
	v_mov_b32_e32 v36, 0
	v_mov_b32_e32 v37, 0
	v_mov_b32_e32 v38, 0
	v_mov_b32_e32 v39, 0
	v_mov_b32_e32 v40, 0
	v_mov_b32_e32 v41, 0
	v_mov_b32_e32 v42, 0
	v_mov_b32_e32 v43, 0
	v_mov_b32_e32 v44, 0
	v_mov_b32_e32 v45, 0
	v_mov_b32_e32 v46, 0
	v_mov_b32_e32 v47, 0
	v_mov_b32_e32 v48, 0
	v_mov_b32_e32 v49, 0
	v_mov_b32_e32 v50, 0
	v_mov_b32_e32 v51, 0
	v_mov_b32_e32 v52, 0
	v_mov_b32_e32 v53, 0
	v_mov_b32_e32 v54, 0
	v_mov_b32_e32 v55, 0
	v_mov_b32_e32 v56, 0
	v_mov_b32_e32 v57, 0
	v_mov_b32_e32 v58, 0
	v_mov_b32_e32 v59, 0
	v_mov_b32_e32 v60, 0
	v_mov_b32_e32 v61, 0
	v_mov_b32_e32 v62, 0
	v_mov_b32_e32 v63, 0
	v_mov_b32_e32 v72, 0
	s_branch .Lxb_join
.Lxf_idle:
	s_and_b32 s0, s21, 0x3fffffc0
	s_lshl_b32 s0, s0, 2
	s_add_i32 s2, s0, 0
	v_mov_b32_e32 v32, v189
	s_branch .Lxf_join

.LBB0_685:
	s_lshl_b32 s0, s88, 6
	s_sub_i32 s0, s0, 0x9f
	s_cmp_gt_i32 s0, s23
	s_cbranch_scc1 .Lxf_idle
	v_add_u32_e32 v164, s4, v190
	ds_read_b64_tr_b16 v[160:161], v164 offset:24576
	ds_read_b64_tr_b16 v[162:163], v164 offset:25088
	v_add_f32_e32 v64, v48, v49
	v_add_f32_e32 v64, v50, v64
	v_add_f32_e32 v64, v51, v64
	v_add_f32_e32 v64, v52, v64
	v_add_f32_e32 v80, v53, v64
	v_mfma_f32_32x32x16_bf16 v[64:79], v[156:159], v[124:127], 0
	v_cvt_pk_bf16_f32 v116, v48, v49
	v_cvt_pk_bf16_f32 v117, v50, v51
	ds_read_b64_tr_b16 v[156:157], v164 offset:28672
	ds_read_b64_tr_b16 v[158:159], v164 offset:29184
	v_add_f32_e32 v48, v54, v80
	v_mfma_f32_32x32x16_bf16 v[80:95], v[148:151], v[124:127], 0
	v_add_f32_e32 v48, v55, v48
	v_add_f32_e32 v48, v56, v48
	v_add_f32_e32 v96, v57, v48
	v_cvt_pk_bf16_f32 v118, v52, v53
	v_cvt_pk_bf16_f32 v119, v54, v55
	ds_read_b64_tr_b16 v[48:49], v164 offset:25600
	ds_read_b64_tr_b16 v[50:51], v164 offset:26112
	v_mfma_f32_32x32x16_bf16 v[64:79], v[152:155], v[120:123], v[64:79]
	v_add_f32_e32 v52, v58, v96
	v_add_f32_e32 v52, v59, v52
	v_add_f32_e32 v52, v60, v52
	v_add_f32_e32 v96, v61, v52
	v_cvt_pk_bf16_f32 v108, v56, v57
	v_cvt_pk_bf16_f32 v109, v58, v59
	ds_read_b64_tr_b16 v[52:53], v164 offset:29696
	ds_read_b64_tr_b16 v[54:55], v164 offset:30208
	v_mfma_f32_32x32x16_bf16 v[80:95], v[144:147], v[120:123], v[80:95]
	v_add_f32_e32 v56, v62, v96
	v_add_f32_e32 v56, v63, v56
	v_add_f32_e32 v56, v32, v56
	v_add_f32_e32 v96, v33, v56
	v_cvt_pk_bf16_f32 v110, v60, v61
	v_cvt_pk_bf16_f32 v111, v62, v63
	ds_read_b64_tr_b16 v[56:57], v164 offset:26624
	ds_read_b64_tr_b16 v[58:59], v164 offset:27136
	v_mfma_f32_32x32x16_bf16 v[64:79], v[140:143], v[112:115], v[64:79]
	v_add_f32_e32 v60, v34, v96
	v_add_f32_e32 v60, v35, v60
	v_add_f32_e32 v60, v36, v60
	v_add_f32_e32 v60, v37, v60
	v_cvt_pk_bf16_f32 v100, v32, v33
	v_cvt_pk_bf16_f32 v101, v34, v35
	ds_read_b64_tr_b16 v[32:33], v164 offset:30720
	ds_read_b64_tr_b16 v[34:35], v164 offset:31232
	v_mfma_f32_32x32x16_bf16 v[80:95], v[136:139], v[112:115], v[80:95]
	v_add_f32_e32 v60, v38, v60
	v_add_f32_e32 v60, v39, v60
	v_add_f32_e32 v60, v40, v60
	v_add_f32_e32 v60, v41, v60
	v_cvt_pk_bf16_f32 v102, v36, v37
	v_cvt_pk_bf16_f32 v103, v38, v39
	ds_read_b64_tr_b16 v[36:37], v164 offset:27648
	ds_read_b64_tr_b16 v[38:39], v164 offset:28160
	v_mfma_f32_32x32x16_bf16 v[64:79], v[132:135], v[104:107], v[64:79]
	v_add_f32_e32 v60, v42, v60
	v_add_f32_e32 v60, v43, v60
	v_add_f32_e32 v60, v44, v60
	v_add_f32_e32 v60, v45, v60
	v_cvt_pk_bf16_f32 v96, v40, v41
	v_cvt_pk_bf16_f32 v97, v42, v43
	ds_read_b64_tr_b16 v[40:41], v164 offset:31744
	ds_read_b64_tr_b16 v[42:43], v164 offset:32256
	v_mfma_f32_32x32x16_bf16 v[80:95], v[128:131], v[104:107], v[80:95]
	v_add_f32_e32 v60, v46, v60
	v_add_f32_e32 v60, v47, v60
	v_add_f32_e32 v60, 0, v60
	v_cvt_pk_bf16_f32 v98, v44, v45
	v_cvt_pk_bf16_f32 v99, v46, v47
	s_lshl_b32 s0, s88, 6
	s_sub_i32 s4, s0, 64
	v_or_b32_e32 v129, s4, v184
	s_add_i32 s0, s0, -1
	s_cmp_le_i32 s0, s23
	v_or_b32_e32 v135, 32, v129
	v_or_b32_e32 v134, 33, v129
	v_or_b32_e32 v132, 2, v129
	v_or_b32_e32 v133, 34, v129
	v_or_b32_e32 v130, 3, v129
	v_or_b32_e32 v131, 35, v129
	v_or_b32_e32 v127, 8, v129
	v_or_b32_e32 v128, 40, v129
	v_or_b32_e32 v125, 9, v129
	v_or_b32_e32 v126, 41, v129
	v_or_b32_e32 v123, 10, v129
	v_or_b32_e32 v124, 42, v129
	v_or_b32_e32 v121, 11, v129
	v_or_b32_e32 v122, 43, v129
	v_or_b32_e32 v115, 16, v129
	v_or_b32_e32 v120, 48, v129
	v_or_b32_e32 v113, 17, v129
	v_or_b32_e32 v114, 49, v129
	v_or_b32_e32 v107, 18, v129
	v_or_b32_e32 v112, 50, v129
	v_or_b32_e32 v105, 19, v129
	v_or_b32_e32 v106, 51, v129
	v_or_b32_e32 v63, 24, v129
	v_or_b32_e32 v104, 56, v129
	v_or_b32_e32 v61, 25, v129
	v_or_b32_e32 v62, 57, v129
	v_or_b32_e32 v46, 26, v129
	v_or_b32_e32 v47, 58, v129
	v_or_b32_e32 v44, 27, v129
	v_or_b32_e32 v45, 59, v129
	s_cbranch_scc1 .LBB0_689
	v_cmp_le_i32_e64 s[0:1], v135, v186
	v_cmp_le_i32_e64 s[38:39], v134, v186
	v_cmp_le_i32_e64 s[40:41], v133, v186
	v_cmp_le_i32_e64 s[42:43], v131, v186
	v_cmp_le_i32_e64 s[44:45], v128, v186
	v_cmp_le_i32_e64 s[46:47], v126, v186
	v_cmp_le_i32_e64 s[50:51], v124, v186
	v_cmp_le_i32_e64 s[52:53], v122, v186
	v_cmp_le_i32_e64 s[54:55], v120, v186
	v_cmp_le_i32_e64 s[56:57], v114, v186
	v_cmp_le_i32_e64 s[58:59], v112, v186
	v_cmp_le_i32_e64 s[60:61], v106, v186
	v_cmp_le_i32_e64 s[62:63], v104, v186
	v_cmp_le_i32_e64 s[64:65], v62, v186
	v_cmp_le_i32_e64 s[66:67], v47, v186
	v_cmp_le_i32_e32 vcc, v129, v186
	v_cndmask_b32_e64 v80, v240, v80, s[0:1]
	v_cmp_lt_i32_e64 s[0:1], v129, v186
	v_cndmask_b32_e64 v81, v240, v81, s[38:39]
	v_cmp_le_i32_e64 s[38:39], v132, v186
	v_cndmask_b32_e64 v82, v240, v82, s[40:41]
	v_cmp_le_i32_e64 s[40:41], v130, v186
	v_cndmask_b32_e64 v83, v240, v83, s[42:43]
	v_cmp_le_i32_e64 s[42:43], v127, v186
	v_cndmask_b32_e64 v84, v240, v84, s[44:45]
	v_cmp_le_i32_e64 s[44:45], v125, v186
	v_cndmask_b32_e64 v85, v240, v85, s[46:47]
	v_cmp_le_i32_e64 s[46:47], v123, v186
	v_cndmask_b32_e64 v86, v240, v86, s[50:51]
	v_cmp_le_i32_e64 s[50:51], v121, v186
	v_cndmask_b32_e64 v87, v240, v87, s[52:53]
	v_cmp_le_i32_e64 s[52:53], v115, v186
	v_cndmask_b32_e64 v88, v240, v88, s[54:55]
	v_cmp_le_i32_e64 s[54:55], v113, v186
	v_cndmask_b32_e64 v89, v240, v89, s[56:57]
	v_cmp_le_i32_e64 s[56:57], v107, v186
	v_cndmask_b32_e64 v90, v240, v90, s[58:59]
	v_cmp_le_i32_e64 s[58:59], v105, v186
	v_cndmask_b32_e64 v91, v240, v91, s[60:61]
	v_cmp_le_i32_e64 s[60:61], v63, v186
	v_cndmask_b32_e64 v92, v240, v92, s[62:63]
	v_cmp_le_i32_e64 s[62:63], v61, v186
	v_cndmask_b32_e64 v93, v240, v93, s[64:65]
	v_cmp_le_i32_e64 s[64:65], v46, v186
	v_cndmask_b32_e64 v94, v240, v94, s[66:67]
	v_cmp_le_i32_e64 s[66:67], v44, v186
	v_cmp_gt_i32_e64 s[68:69], v45, v186
	s_and_saveexec_b64 s[2:3], s[68:69]
	s_mov_b32 s5, 0xff800000
	v_mov_b32_e32 v95, s5
	s_or_b64 exec, exec, s[2:3]
	v_cndmask_b32_e64 v65, v240, v65, s[0:1]
	v_cndmask_b32_e32 v64, v240, v64, vcc
	v_cndmask_b32_e64 v66, v240, v66, s[38:39]
	v_cndmask_b32_e64 v67, v240, v67, s[40:41]
	v_cndmask_b32_e64 v68, v240, v68, s[42:43]
	v_cndmask_b32_e64 v69, v240, v69, s[44:45]
	v_cndmask_b32_e64 v70, v240, v70, s[46:47]
	v_cndmask_b32_e64 v71, v240, v71, s[50:51]
	v_cndmask_b32_e64 v72, v240, v72, s[52:53]
	v_cndmask_b32_e64 v73, v240, v73, s[54:55]
	v_cndmask_b32_e64 v74, v240, v74, s[56:57]
	v_cndmask_b32_e64 v75, v240, v75, s[58:59]
	v_cndmask_b32_e64 v76, v240, v76, s[60:61]
	v_cndmask_b32_e64 v77, v240, v77, s[62:63]
	v_cndmask_b32_e64 v78, v240, v78, s[64:65]
	v_cndmask_b32_e64 v79, v240, v79, s[66:67]

.Lxf_join:
	v_mov_b32_e32 v33, v32
	s_nop 1
	v_permlane32_swap_b32_e32 v32, v33
	v_cmp_gt_u32_e32 vcc, 32, v192
	s_and_saveexec_b64 s[0:1], vcc
	s_cbranch_execz .LBB0_524
	v_add_f32_e32 v34, v32, v33
	v_log_f32_e32 v32, v34
	s_and_b64 s[4:5], s[8:9], exec
	v_ashrrev_i32_e32 v175, 31, v174
	s_cselect_b32 s3, 4, 6
	v_add_f32_e32 v35, 0, v32
	v_lshlrev_b64 v[32:33], s3, v[174:175]
	v_lshl_add_u64 v[32:33], v[32:33], 2, s[10:11]
	global_store_dword v[32:33], v35, off
	v_lshl_add_u32 v32, v182, 2, s2
	ds_write_b32 v32, v34 offset:49280
	s_branch .LBB0_524
